# grid barrier (in-layer instances): hand-written thread-0 path, every workgroup polls the cross-XCD arrival counter for the round's final count; no TOPGEN/XGEN hops
# speedup vs baseline: 1.0077x; 1.0072x over previous
.LBB0_263:
	s_waitcnt vmcnt(0)
	s_waitcnt vmcnt(0) lgkmcnt(0)
	s_barrier
	s_getreg_b32 s0, hwreg(HW_REG_HW_ID, 0, 6)
	s_and_b32 s0, s0, 63
	s_lshl_b32 s0, s0, 2
	s_add_i32 s0, s0, 0
	s_add_i32 s0, s0, 0x20400
	v_mov_b32_e32 v0, s0
	ds_read_b32 v0, v0
	s_waitcnt lgkmcnt(0)
	v_readfirstlane_b32 s0, v0
	v_mbcnt_lo_u32_b32 v0, -1, 0
	v_mbcnt_hi_u32_b32 v0, -1, v0
	s_lshl_b32 s0, s0, 6
	v_sub_u32_e32 v0, 0, v0
	v_cmp_eq_u32_e32 vcc, s0, v0
	s_and_saveexec_b64 s[2:3], vcc
	s_cbranch_execz .LBB0_315
	v_readlane_b32 s0, v255, 16
	s_waitcnt vmcnt(0) expcnt(0) lgkmcnt(0)
	v_mov_b32_e32 v7, 0
	v_mov_b32_e32 v0, s0
	ds_read_b32 v3, v0
	v_readlane_b32 s0, v255, 17
	v_mov_b32_e32 v4, 1
	v_readlane_b32 s4, v255, 7
	v_readlane_b32 s5, v255, 8
	v_mov_b32_e32 v0, s0
	ds_read_b32 v2, v0
	s_nop 2
	global_atomic_add v4, v7, v4, s[4:5] sc0
	v_readlane_b32 s4, v255, 11
	v_readlane_b32 s5, v255, 12
	s_waitcnt lgkmcnt(0)
	v_cvt_f32_u32_e32 v5, v3
	v_sub_u32_e32 v6, 0, v3
	v_rcp_iflag_f32_e32 v5, v5
	s_nop 0
	v_mul_f32_e32 v5, 0x4f7ffffe, v5
	v_cvt_u32_f32_e32 v5, v5
	v_mul_lo_u32 v0, v6, v5
	v_mul_hi_u32 v0, v5, v0
	v_add_u32_e32 v0, v5, v0
	s_waitcnt vmcnt(0)
	v_mul_hi_u32 v0, v4, v0
	v_mul_lo_u32 v6, v0, v3
	v_sub_u32_e32 v6, v4, v6
	v_cmp_ge_u32_e32 vcc, v6, v3
	v_add_u32_e32 v5, 1, v0
	s_nop 0
	v_cndmask_b32_e32 v0, v0, v5, vcc
	v_sub_u32_e32 v5, v6, v3
	v_cndmask_b32_e32 v6, v6, v5, vcc
	v_cmp_ge_u32_e32 vcc, v6, v3
	v_add_u32_e32 v5, 1, v0
	s_nop 0
	v_cndmask_b32_e32 v0, v0, v5, vcc
	v_add_u32_e32 v5, 1, v0
	v_mul_lo_u32 v6, v5, v3
	v_mul_lo_u32 v5, v5, v2
	v_add_u32_e32 v4, 1, v4
	v_cmp_eq_u32_e32 vcc, v4, v6
	s_cbranch_vccz .Lbarf_poll0
	buffer_wbl2 sc1
	v_mov_b32_e32 v4, 1
	s_waitcnt vmcnt(0)
	global_atomic_add v7, v4, s[4:5]
.Lbarf_poll0:
	s_mov_b32 s0, 0
.Lbarf_spin0:
	global_load_dword v6, v7, s[4:5] sc1
	s_waitcnt vmcnt(0)
	v_cmp_ge_u32_e32 vcc, v6, v5
	s_cbranch_vccnz .Lbarf_done0
	s_sleep 1
	s_add_u32 s0, s0, 1
	s_cmp_lt_u32 s0, 0x40000
	s_cbranch_scc1 .Lbarf_spin0
	v_readlane_b32 s6, v254, 5
	v_readlane_b32 s7, v254, 6
	v_mov_b32_e32 v4, 1
	s_nop 3
	global_atomic_add v7, v4, s[6:7]
.Lbarf_done0:
	s_waitcnt vmcnt(0)
	buffer_inv sc1
	s_waitcnt vmcnt(0)

.Lma_seam:
	s_waitcnt vmcnt(0)
	s_barrier
	s_getreg_b32 s0, hwreg(HW_REG_HW_ID, 0, 6)
	s_and_b32 s0, s0, 63
	s_lshl_b32 s0, s0, 2
	s_add_i32 s0, s0, 0
	s_add_i32 s0, s0, 0x20400
	v_mov_b32_e32 v0, s0
	ds_read_b32 v0, v0
	s_waitcnt lgkmcnt(0)
	v_readfirstlane_b32 s0, v0
	v_mbcnt_lo_u32_b32 v0, -1, 0
	v_mbcnt_hi_u32_b32 v0, -1, v0
	s_lshl_b32 s0, s0, 6
	v_sub_u32_e32 v0, 0, v0
	v_cmp_eq_u32_e32 vcc, s0, v0
	s_and_saveexec_b64 s[2:3], vcc
	s_cbranch_execz .LBB0_542
	v_readlane_b32 s0, v255, 16
	s_waitcnt vmcnt(0) expcnt(0) lgkmcnt(0)
	v_mov_b32_e32 v7, 0
	v_mov_b32_e32 v0, s0
	ds_read_b32 v3, v0
	v_readlane_b32 s0, v255, 17
	v_mov_b32_e32 v4, 1
	v_readlane_b32 s4, v255, 7
	v_readlane_b32 s5, v255, 8
	v_mov_b32_e32 v0, s0
	ds_read_b32 v2, v0
	s_nop 2
	global_atomic_add v4, v7, v4, s[4:5] sc0
	v_readlane_b32 s4, v255, 11
	v_readlane_b32 s5, v255, 12
	s_waitcnt lgkmcnt(0)
	v_cvt_f32_u32_e32 v5, v3
	v_sub_u32_e32 v6, 0, v3
	v_rcp_iflag_f32_e32 v5, v5
	s_nop 0
	v_mul_f32_e32 v5, 0x4f7ffffe, v5
	v_cvt_u32_f32_e32 v5, v5
	v_mul_lo_u32 v0, v6, v5
	v_mul_hi_u32 v0, v5, v0
	v_add_u32_e32 v0, v5, v0
	s_waitcnt vmcnt(0)
	v_mul_hi_u32 v0, v4, v0
	v_mul_lo_u32 v6, v0, v3
	v_sub_u32_e32 v6, v4, v6
	v_cmp_ge_u32_e32 vcc, v6, v3
	v_add_u32_e32 v5, 1, v0
	s_nop 0
	v_cndmask_b32_e32 v0, v0, v5, vcc
	v_sub_u32_e32 v5, v6, v3
	v_cndmask_b32_e32 v6, v6, v5, vcc
	v_cmp_ge_u32_e32 vcc, v6, v3
	v_add_u32_e32 v5, 1, v0
	s_nop 0
	v_cndmask_b32_e32 v0, v0, v5, vcc
	v_add_u32_e32 v5, 1, v0
	v_mul_lo_u32 v6, v5, v3
	v_mul_lo_u32 v5, v5, v2
	v_add_u32_e32 v4, 1, v4
	v_cmp_eq_u32_e32 vcc, v4, v6
	s_cbranch_vccz .Lbarf_poll1
	buffer_wbl2 sc1
	v_mov_b32_e32 v4, 1
	s_waitcnt vmcnt(0)
	global_atomic_add v7, v4, s[4:5]

.LBB0_1650:
	v_readlane_b32 s0, v255, 16
	s_waitcnt vmcnt(0) expcnt(0) lgkmcnt(0)
	v_mov_b32_e32 v7, 0
	v_mov_b32_e32 v0, s0
	ds_read_b32 v3, v0
	v_readlane_b32 s0, v255, 17
	v_mov_b32_e32 v4, 1
	v_readlane_b32 s4, v255, 7
	v_readlane_b32 s5, v255, 8
	v_mov_b32_e32 v0, s0
	ds_read_b32 v2, v0
	s_nop 2
	global_atomic_add v4, v7, v4, s[4:5] sc0
	v_readlane_b32 s4, v255, 11
	v_readlane_b32 s5, v255, 12
	s_waitcnt lgkmcnt(0)
	v_cvt_f32_u32_e32 v5, v3
	v_sub_u32_e32 v6, 0, v3
	v_rcp_iflag_f32_e32 v5, v5
	s_nop 0
	v_mul_f32_e32 v5, 0x4f7ffffe, v5
	v_cvt_u32_f32_e32 v5, v5
	v_mul_lo_u32 v0, v6, v5
	v_mul_hi_u32 v0, v5, v0
	v_add_u32_e32 v0, v5, v0
	s_waitcnt vmcnt(0)
	v_mul_hi_u32 v0, v4, v0
	v_mul_lo_u32 v6, v0, v3
	v_sub_u32_e32 v6, v4, v6
	v_cmp_ge_u32_e32 vcc, v6, v3
	v_add_u32_e32 v5, 1, v0
	s_nop 0
	v_cndmask_b32_e32 v0, v0, v5, vcc
	v_sub_u32_e32 v5, v6, v3
	v_cndmask_b32_e32 v6, v6, v5, vcc
	v_cmp_ge_u32_e32 vcc, v6, v3
	v_add_u32_e32 v5, 1, v0
	s_nop 0
	v_cndmask_b32_e32 v0, v0, v5, vcc
	v_add_u32_e32 v5, 1, v0
	v_mul_lo_u32 v6, v5, v3
	v_mul_lo_u32 v5, v5, v2
	v_add_u32_e32 v4, 1, v4
	v_cmp_eq_u32_e32 vcc, v4, v6
	s_cbranch_vccz .Lbarf_poll7
	buffer_wbl2 sc1
	v_mov_b32_e32 v4, 1
	s_waitcnt vmcnt(0)
	global_atomic_add v7, v4, s[4:5]

.Lbarf_done7:
	s_waitcnt vmcnt(0)
	buffer_inv sc1
	s_waitcnt vmcnt(0)
	s_getpc_b64 s[98:99]
